# v28 + LRU pass-1 conv-row warm-up also two sub-tiles ahead
# baseline (speedup 1.0000x reference)
; template <int PASS> __device__ __forceinline__ void lru_wave_item(LAS unsigned char* lds, LAS unsigned char* vw, int b, int c, int h, const MixP& p, int lane, float (&Hrun)[8], bool cont) {
;     ...
;     const bf16_t* ub = p.P1 + (size_t)(b * SEQ) * P1W + PW + h * 128 + cg * 8;
; #pragma unroll 1
;     for (int st = 0; st < CT / 16; ++st) {
;         const int s0 = c * CT + 16 * st;
;         u32x4 ur[7];
;         {
;             const int sb = s0 + 4 * fq - 3;
; #pragma unroll
;             for (int r = 0; r < 7; ++r) ur[r] = *(const u32x4*)(ub + (size_t)max(sb + r, 0) * P1W);
;         }
;         if (s0 == 0 && fq == 0) {
; #pragma unroll
;             for (int r = 0; r < 3; ++r) ur[r] = (u32x4){0u, 0u, 0u, 0u};
;         }
.LBB0_668:
	s_or_b32 s2, s19, s13
	v_add_u32_e32 v74, s2, v230
	v_cndmask_b32_e64 v50, 0, 1, s[28:29]
	v_max_i32_e32 v54, -1, v74
	v_cmp_ne_u32_e32 vcc, 1, v50
	v_max_i32_e32 v50, 0, v74
	v_add_u32_e32 v54, 1, v54
	v_or_b32_e32 v58, 2, v74
	v_mad_u64_u32 v[50:51], s[20:21], v50, s82, v[196:197]
	v_mad_u64_u32 v[54:55], s[20:21], v54, s82, v[196:197]
	v_max_i32_e32 v58, 0, v58
	global_load_dwordx4 v[50:53], v[50:51], off offset:1024
	v_mad_u64_u32 v[58:59], s[20:21], v58, s82, v[196:197]
	global_load_dwordx4 v[54:57], v[54:55], off offset:1024
	v_or_b32_e32 v62, s2, v229
	global_load_dwordx4 v[58:61], v[58:59], off offset:1024
	v_max_i32_e32 v62, 0, v62
	v_mad_u64_u32 v[62:63], s[20:21], v62, s82, v[196:197]
	global_load_dwordx4 v[62:65], v[62:63], off offset:1024
	v_max_i32_e32 v66, -4, v74
	v_add_u32_e32 v66, 4, v66
	v_mad_u64_u32 v[66:67], s[20:21], v66, s82, v[196:197]
	global_load_dwordx4 v[66:69], v[66:67], off offset:1024
	v_max_i32_e32 v70, -5, v74
	v_add_u32_e32 v70, 5, v70
	v_mad_u64_u32 v[70:71], s[20:21], v70, s82, v[196:197]
	global_load_dwordx4 v[70:73], v[70:71], off offset:1024
	v_max_i32_e32 v74, -6, v74
	v_add_u32_e32 v74, 6, v74
	v_mad_u64_u32 v[74:75], s[20:21], v74, s82, v[196:197]
	global_load_dwordx4 v[74:77], v[74:75], off offset:1024
	s_add_i32 s100, s2, 16
	v_add_u32_e32 v92, s100, v230
	v_max_i32_e32 v93, 0, v92
	v_mad_u64_u32 v[94:95], s[98:99], v93, s82, v[196:197]
	global_load_dword v206, v[94:95], off offset:1024
	v_add_u32_e32 v93, 1, v92
	v_max_i32_e32 v93, 0, v93
	v_mad_u64_u32 v[94:95], s[98:99], v93, s82, v[196:197]
	global_load_dword v206, v[94:95], off offset:1024
	v_add_u32_e32 v93, 2, v92
	v_max_i32_e32 v93, 0, v93
	v_mad_u64_u32 v[94:95], s[98:99], v93, s82, v[196:197]
	global_load_dword v206, v[94:95], off offset:1024
	v_add_u32_e32 v93, 3, v92
	v_max_i32_e32 v93, 0, v93
	v_mad_u64_u32 v[94:95], s[98:99], v93, s82, v[196:197]
	global_load_dword v206, v[94:95], off offset:1024
	v_add_u32_e32 v93, 4, v92
	v_max_i32_e32 v93, 0, v93
	v_mad_u64_u32 v[94:95], s[98:99], v93, s82, v[196:197]
	global_load_dword v206, v[94:95], off offset:1024
	v_add_u32_e32 v93, 5, v92
	v_max_i32_e32 v93, 0, v93
	v_mad_u64_u32 v[94:95], s[98:99], v93, s82, v[196:197]
	global_load_dword v206, v[94:95], off offset:1024
	v_add_u32_e32 v93, 6, v92
	v_max_i32_e32 v93, 0, v93
	v_mad_u64_u32 v[94:95], s[98:99], v93, s82, v[196:197]
	global_load_dword v206, v[94:95], off offset:1024
	s_add_i32 s100, s2, 32
	v_add_u32_e32 v92, s100, v230
	v_max_i32_e32 v93, 0, v92
	v_mad_u64_u32 v[94:95], s[98:99], v93, s82, v[196:197]
	global_load_dword v206, v[94:95], off offset:1024
	v_add_u32_e32 v93, 1, v92
	v_max_i32_e32 v93, 0, v93
	v_mad_u64_u32 v[94:95], s[98:99], v93, s82, v[196:197]
	global_load_dword v206, v[94:95], off offset:1024
	v_add_u32_e32 v93, 2, v92
	v_max_i32_e32 v93, 0, v93
	v_mad_u64_u32 v[94:95], s[98:99], v93, s82, v[196:197]
	global_load_dword v206, v[94:95], off offset:1024
	v_add_u32_e32 v93, 3, v92
	v_max_i32_e32 v93, 0, v93
	v_mad_u64_u32 v[94:95], s[98:99], v93, s82, v[196:197]
	global_load_dword v206, v[94:95], off offset:1024
	v_add_u32_e32 v93, 4, v92
	v_max_i32_e32 v93, 0, v93
	v_mad_u64_u32 v[94:95], s[98:99], v93, s82, v[196:197]
	global_load_dword v206, v[94:95], off offset:1024
	v_add_u32_e32 v93, 5, v92
	v_max_i32_e32 v93, 0, v93
	v_mad_u64_u32 v[94:95], s[98:99], v93, s82, v[196:197]
	global_load_dword v206, v[94:95], off offset:1024
	v_add_u32_e32 v93, 6, v92
	v_max_i32_e32 v93, 0, v93
	v_mad_u64_u32 v[94:95], s[98:99], v93, s82, v[196:197]
	global_load_dword v206, v[94:95], off offset:1024
	s_cmp_eq_u32 s2, 0
	s_cselect_b64 s[16:17], -1, 0
	s_and_b64 s[16:17], s[16:17], s[4:5]
	v_add_u32_e32 v138, v234, v231
	s_mov_b32 s19, 16
	s_mov_b64 s[28:29], 0
	s_and_b64 vcc, exec, vcc
	s_waitcnt vmcnt(19)
	v_cndmask_b32_e64 v81, v57, 0, s[16:17]
	v_cndmask_b32_e64 v57, v53, 0, s[16:17]
	v_cndmask_b32_e64 v53, v51, 0, s[16:17]
	v_cndmask_b32_e64 v51, v50, 0, s[16:17]
	s_waitcnt vmcnt(18)
	v_cndmask_b32_e64 v85, v59, 0, s[16:17]
	v_cndmask_b32_e64 v59, v54, 0, s[16:17]
	v_lshlrev_b32_e32 v50, 16, v51
	v_and_b32_e32 v51, 0xffff0000, v51
	v_cndmask_b32_e64 v89, v61, 0, s[16:17]
	v_cndmask_b32_e64 v83, v58, 0, s[16:17]
	v_cndmask_b32_e64 v61, v55, 0, s[16:17]
	v_cndmask_b32_e64 v55, v52, 0, s[16:17]
	s_waitcnt lgkmcnt(13)
	v_pk_fma_f32 v[50:51], v[10:11], v[50:51], v[42:43]
	v_lshlrev_b32_e32 v52, 16, v53
	v_and_b32_e32 v53, 0xffff0000, v53
	v_lshlrev_b32_e32 v58, 16, v59
	v_and_b32_e32 v59, 0xffff0000, v59
	v_cndmask_b32_e64 v87, v60, 0, s[16:17]
	v_cndmask_b32_e64 v79, v56, 0, s[16:17]
	v_pk_fma_f32 v[52:53], v[12:13], v[52:53], v[44:45]
	v_lshlrev_b32_e32 v54, 16, v55
	v_and_b32_e32 v55, 0xffff0000, v55
	v_lshlrev_b32_e32 v56, 16, v57
	v_and_b32_e32 v57, 0xffff0000, v57
	v_pk_fma_f32 v[50:51], v[18:19], v[58:59], v[50:51]
	v_lshlrev_b32_e32 v60, 16, v61
	v_and_b32_e32 v61, 0xffff0000, v61
	v_lshlrev_b32_e32 v82, 16, v83
	v_and_b32_e32 v83, 0xffff0000, v83
	s_waitcnt lgkmcnt(12)
	v_pk_fma_f32 v[54:55], v[14:15], v[54:55], v[46:47]
	v_pk_fma_f32 v[56:57], v[16:17], v[56:57], v[48:49]
	v_pk_fma_f32 v[52:53], v[20:21], v[60:61], v[52:53]
	v_lshlrev_b32_e32 v78, 16, v79
	v_and_b32_e32 v79, 0xffff0000, v79
	v_lshlrev_b32_e32 v80, 16, v81
	v_and_b32_e32 v81, 0xffff0000, v81
	v_pk_fma_f32 v[50:51], v[26:27], v[82:83], v[50:51]
	v_lshlrev_b32_e32 v84, 16, v85
	v_and_b32_e32 v85, 0xffff0000, v85
	s_waitcnt vmcnt(17)
; #define LAS __attribute__((address_space(3)))
; __device__ __forceinline__ unsigned cvt_pk_bf16(float lo, float hi) { unsigned r; asm volatile("v_cvt_pk_bf16_f32 %0, %1, %2" : "=v"(r) : "v"(lo), "v"(hi)); return r; }
; __device__ __forceinline__ float bflo(unsigned w) { return __uint_as_float(w << 16); }
; __device__ __forceinline__ float bfhi(unsigned w) { return __uint_as_float(w & 0xffff0000u); }
; template <int PASS> __device__ __forceinline__ void lru_wave_item(LAS unsigned char* lds, LAS unsigned char* vw, int b, int c, int h, const MixP& p, int lane, float (&Hrun)[8], bool cont) {
;     ...
; #pragma unroll
;         for (int jj = 0; jj < 4; ++jj) {
;             f32x2 o[4] = {bv[0], bv[1], bv[2], bv[3]};
; #pragma unroll
;             for (int k = 0; k < 4; ++k) { const u32x4 uk = ur[jj + k];
;                 o[0] = wv[k][0] * (f32x2){bflo(uk.x), bfhi(uk.x)} + o[0]; o[1] = wv[k][1] * (f32x2){bflo(uk.y), bfhi(uk.y)} + o[1];
;                 o[2] = wv[k][2] * (f32x2){bflo(uk.z), bfhi(uk.z)} + o[2]; o[3] = wv[k][3] * (f32x2){bflo(uk.w), bfhi(uk.w)} + o[3]; }
;             { u32x4 w; w.x = cvt_pk_bf16(o[0].x, o[0].y); w.y = cvt_pk_bf16(o[1].x, o[1].y); w.z = cvt_pk_bf16(o[2].x, o[2].y); w.w = cvt_pk_bf16(o[3].x, o[3].y);
;               *(LAS u32x4*)(vw + (4 * fq + jj) * WROW + cg * 16) = w; }
;         }
;         f32x4 aR[8], aI[8];
;         bf16x8 af[4];
;         {
; #pragma unroll
;             for (int kk = 0; kk < 4; ++kk) af[kk] = *(const LAS bf16x8*)(vw + fr * WROW + kk * 64 + fq * 16);
; #pragma unroll
;             for (int n = 0; n < 8; ++n) {
;                 aR[n] = (f32x4){0.f, 0.f, 0.f, 0.f}; aI[n] = (f32x4){0.f, 0.f, 0.f, 0.f};
; #pragma unroll
;                 for (int kk = 0; kk < 4; ++kk) {
;                     const bf16x8 ba = *(const LAS bf16x8*)(lds + WA_OFF + (16 * n + fr) * WROW + kk * 64 + fq * 16);
;                     const bf16x8 bx = *(const LAS bf16x8*)(lds + WX_OFF + (16 * n + fr) * WROW + kk * 64 + fq * 16);
;                     aR[n] = __builtin_amdgcn_mfma_f32_16x16x32_bf16(af[kk], ba, aR[n], 0, 0, 0);
;                     aI[n] = __builtin_amdgcn_mfma_f32_16x16x32_bf16(af[kk], bx, aI[n], 0, 0, 0);
	v_lshlrev_b32_e32 v90, 16, v62
	v_and_b32_e32 v91, 0xffff0000, v62
	v_pk_fma_f32 v[54:55], v[22:23], v[78:79], v[54:55]
	v_pk_fma_f32 v[56:57], v[24:25], v[80:81], v[56:57]
	v_pk_fma_f32 v[52:53], v[28:29], v[84:85], v[52:53]
	v_lshlrev_b32_e32 v86, 16, v87
	v_and_b32_e32 v87, 0xffff0000, v87
	v_lshlrev_b32_e32 v88, 16, v89
	v_and_b32_e32 v89, 0xffff0000, v89
	v_pk_fma_f32 v[50:51], v[34:35], v[90:91], v[50:51]
	v_lshlrev_b32_e32 v62, 16, v63
	v_and_b32_e32 v63, 0xffff0000, v63
	v_pk_fma_f32 v[54:55], v[30:31], v[86:87], v[54:55]
	v_pk_fma_f32 v[56:57], v[32:33], v[88:89], v[56:57]
	v_pk_fma_f32 v[52:53], v[36:37], v[62:63], v[52:53]
	v_lshlrev_b32_e32 v92, 16, v64
	v_and_b32_e32 v93, 0xffff0000, v64
	v_lshlrev_b32_e32 v64, 16, v65
	v_and_b32_e32 v65, 0xffff0000, v65
	v_cvt_pk_bf16_f32 v50, v50, v51
	v_cvt_pk_bf16_f32 v51, v52, v53
	v_pk_fma_f32 v[54:55], v[38:39], v[92:93], v[54:55]
	v_pk_fma_f32 v[56:57], v[40:41], v[64:65], v[56:57]
	v_cvt_pk_bf16_f32 v52, v54, v55
	v_pk_fma_f32 v[54:55], v[14:15], v[78:79], v[46:47]
	v_cvt_pk_bf16_f32 v53, v56, v57
	ds_write_b128 v247, v[50:53]
	v_pk_fma_f32 v[50:51], v[10:11], v[58:59], v[42:43]
	v_pk_fma_f32 v[52:53], v[12:13], v[60:61], v[44:45]
	v_pk_fma_f32 v[50:51], v[18:19], v[82:83], v[50:51]
	v_pk_fma_f32 v[56:57], v[16:17], v[80:81], v[48:49]
	v_pk_fma_f32 v[52:53], v[20:21], v[84:85], v[52:53]
	v_pk_fma_f32 v[50:51], v[26:27], v[90:91], v[50:51]
	s_waitcnt vmcnt(16)
	v_lshlrev_b32_e32 v58, 16, v66
	v_and_b32_e32 v59, 0xffff0000, v66
	v_pk_fma_f32 v[54:55], v[22:23], v[86:87], v[54:55]
	v_pk_fma_f32 v[56:57], v[24:25], v[88:89], v[56:57]
	v_pk_fma_f32 v[52:53], v[28:29], v[62:63], v[52:53]
	v_pk_fma_f32 v[50:51], v[34:35], v[58:59], v[50:51]
	v_lshlrev_b32_e32 v60, 16, v67
	v_and_b32_e32 v61, 0xffff0000, v67
	v_pk_fma_f32 v[54:55], v[30:31], v[92:93], v[54:55]
	v_pk_fma_f32 v[56:57], v[32:33], v[64:65], v[56:57]
	v_pk_fma_f32 v[52:53], v[36:37], v[60:61], v[52:53]
	v_lshlrev_b32_e32 v66, 16, v68
	v_and_b32_e32 v67, 0xffff0000, v68
	v_lshlrev_b32_e32 v68, 16, v69
	v_and_b32_e32 v69, 0xffff0000, v69
	v_cvt_pk_bf16_f32 v50, v50, v51
	v_cvt_pk_bf16_f32 v51, v52, v53
	v_pk_fma_f32 v[54:55], v[38:39], v[66:67], v[54:55]
	v_pk_fma_f32 v[56:57], v[40:41], v[68:69], v[56:57]
	v_cvt_pk_bf16_f32 v52, v54, v55
	v_pk_fma_f32 v[54:55], v[14:15], v[86:87], v[46:47]
	v_cvt_pk_bf16_f32 v53, v56, v57
	ds_write_b128 v247, v[50:53] offset:272
	v_pk_fma_f32 v[50:51], v[10:11], v[82:83], v[42:43]
	v_pk_fma_f32 v[52:53], v[12:13], v[84:85], v[44:45]
	v_pk_fma_f32 v[50:51], v[18:19], v[90:91], v[50:51]
	v_pk_fma_f32 v[56:57], v[16:17], v[88:89], v[48:49]
	v_pk_fma_f32 v[52:53], v[20:21], v[62:63], v[52:53]
	v_pk_fma_f32 v[50:51], v[26:27], v[58:59], v[50:51]
	s_waitcnt vmcnt(15)
	v_lshlrev_b32_e32 v78, 16, v70
	v_and_b32_e32 v79, 0xffff0000, v70
	v_pk_fma_f32 v[54:55], v[22:23], v[92:93], v[54:55]
	v_pk_fma_f32 v[56:57], v[24:25], v[64:65], v[56:57]
	v_pk_fma_f32 v[52:53], v[28:29], v[60:61], v[52:53]
	v_pk_fma_f32 v[50:51], v[34:35], v[78:79], v[50:51]
	v_lshlrev_b32_e32 v70, 16, v71
	v_and_b32_e32 v71, 0xffff0000, v71
	v_pk_fma_f32 v[54:55], v[30:31], v[66:67], v[54:55]
	v_pk_fma_f32 v[56:57], v[32:33], v[68:69], v[56:57]
	v_pk_fma_f32 v[52:53], v[36:37], v[70:71], v[52:53]
	v_lshlrev_b32_e32 v80, 16, v72
	v_and_b32_e32 v81, 0xffff0000, v72
	v_lshlrev_b32_e32 v72, 16, v73
	v_and_b32_e32 v73, 0xffff0000, v73
	v_cvt_pk_bf16_f32 v50, v50, v51
	v_cvt_pk_bf16_f32 v51, v52, v53
	v_pk_fma_f32 v[54:55], v[38:39], v[80:81], v[54:55]
	v_pk_fma_f32 v[56:57], v[40:41], v[72:73], v[56:57]
	v_cvt_pk_bf16_f32 v52, v54, v55
	v_pk_fma_f32 v[54:55], v[14:15], v[92:93], v[46:47]
	v_cvt_pk_bf16_f32 v53, v56, v57
	ds_write_b128 v247, v[50:53] offset:544
	v_pk_fma_f32 v[50:51], v[10:11], v[90:91], v[42:43]
	v_pk_fma_f32 v[52:53], v[12:13], v[62:63], v[44:45]
	v_pk_fma_f32 v[50:51], v[18:19], v[58:59], v[50:51]
	v_pk_fma_f32 v[52:53], v[20:21], v[60:61], v[52:53]
	v_pk_fma_f32 v[50:51], v[26:27], v[78:79], v[50:51]
	s_waitcnt vmcnt(14)
	v_lshlrev_b32_e32 v58, 16, v74
	v_and_b32_e32 v59, 0xffff0000, v74
	v_pk_fma_f32 v[56:57], v[16:17], v[64:65], v[48:49]
	v_pk_fma_f32 v[54:55], v[22:23], v[66:67], v[54:55]
	v_pk_fma_f32 v[52:53], v[28:29], v[70:71], v[52:53]
	v_pk_fma_f32 v[50:51], v[34:35], v[58:59], v[50:51]
	v_lshlrev_b32_e32 v58, 16, v75
	v_and_b32_e32 v59, 0xffff0000, v75
	v_pk_fma_f32 v[56:57], v[24:25], v[68:69], v[56:57]
	v_pk_fma_f32 v[54:55], v[30:31], v[80:81], v[54:55]
	v_pk_fma_f32 v[52:53], v[36:37], v[58:59], v[52:53]
	v_lshlrev_b32_e32 v58, 16, v76
	v_and_b32_e32 v59, 0xffff0000, v76
	v_pk_fma_f32 v[56:57], v[32:33], v[72:73], v[56:57]
	v_pk_fma_f32 v[54:55], v[38:39], v[58:59], v[54:55]
	v_lshlrev_b32_e32 v58, 16, v77
	v_and_b32_e32 v59, 0xffff0000, v77
	v_cvt_pk_bf16_f32 v50, v50, v51
	v_pk_fma_f32 v[56:57], v[40:41], v[58:59], v[56:57]
	v_cvt_pk_bf16_f32 v51, v52, v53
	v_cvt_pk_bf16_f32 v52, v54, v55
	v_add_u32_e32 v74, v234, v235
	v_cvt_pk_bf16_f32 v53, v56, v57
	ds_write_b128 v247, v[50:53] offset:816
	v_add_u32_e32 v50, v232, v233
	ds_read_b128 v[110:113], v50
	ds_read_b128 v[82:85], v50 offset:64
	ds_read_b128 v[54:57], v50 offset:128
	ds_read_b128 v[50:53], v50 offset:192
	ds_read_b128 v[58:61], v138
	ds_read_b128 v[62:65], v138 offset:34816
	ds_read_b128 v[66:69], v138 offset:64
	ds_read_b128 v[70:73], v138 offset:34880
	s_waitcnt lgkmcnt(3)
	v_mfma_f32_16x16x32_bf16 v[58:61], v[110:113], v[58:61], 0
	s_waitcnt lgkmcnt(2)
	v_mfma_f32_16x16x32_bf16 v[62:65], v[110:113], v[62:65], 0
	s_waitcnt lgkmcnt(1)
	v_mfma_f32_16x16x32_bf16 v[58:61], v[82:85], v[66:69], v[58:61]
	s_waitcnt lgkmcnt(0)
; #define LAS __attribute__((address_space(3)))
; __device__ __forceinline__ float fsig2(float x) { return __builtin_amdgcn_rcpf(1.0f + __builtin_amdgcn_exp2f(-LOG2E * x)); }
; template <int PASS> __device__ __forceinline__ void lru_wave_item(LAS unsigned char* lds, LAS unsigned char* vw, int b, int c, int h, const MixP& p, int lane, float (&Hrun)[8], bool cont) {
;     ...
;             for (int kk = 0; kk < 4; ++kk) af[kk] = *(const LAS bf16x8*)(vw + fr * WROW + kk * 64 + fq * 16);
; #pragma unroll
;             for (int n = 0; n < 8; ++n) {
;                 aR[n] = (f32x4){0.f, 0.f, 0.f, 0.f}; aI[n] = (f32x4){0.f, 0.f, 0.f, 0.f};
; #pragma unroll
;                 for (int kk = 0; kk < 4; ++kk) {
;                     const bf16x8 ba = *(const LAS bf16x8*)(lds + WA_OFF + (16 * n + fr) * WROW + kk * 64 + fq * 16);
;                     const bf16x8 bx = *(const LAS bf16x8*)(lds + WX_OFF + (16 * n + fr) * WROW + kk * 64 + fq * 16);
;                     aR[n] = __builtin_amdgcn_mfma_f32_16x16x32_bf16(af[kk], ba, aR[n], 0, 0, 0);
;                     aI[n] = __builtin_amdgcn_mfma_f32_16x16x32_bf16(af[kk], bx, aI[n], 0, 0, 0);
;                 }
;             }
;         }
; #pragma unroll
;         for (int n = 0; n < 8; ++n) {
;             const f32x4 aVn = __builtin_amdgcn_mfma_f32_16x16x32_bf16(af[n >> 1], idf[n & 1], (f32x4){0.f, 0.f, 0.f, 0.f}, 0, 0, 0);
;             float av[4], bxv[4];
; #pragma unroll
;             for (int j = 0; j < 4; ++j) {
;                 const float r = fsig2(aR[n][j] + pba[n]), ig = fsig2(aI[n][j] + pbx[n]);
;                 const float a = __builtin_amdgcn_exp2f(r * pk8[n]), mult = __builtin_amdgcn_sqrtf(fmaxf(1.0f - a * a, 0.f));
	v_mfma_f32_16x16x32_bf16 v[62:65], v[82:85], v[70:73], v[62:65]
	ds_read_b128 v[66:69], v138 offset:128
	ds_read_b128 v[70:73], v138 offset:34944
	s_waitcnt lgkmcnt(1)
	v_mfma_f32_16x16x32_bf16 v[58:61], v[54:57], v[66:69], v[58:61]
	s_waitcnt lgkmcnt(0)
	v_mfma_f32_16x16x32_bf16 v[62:65], v[54:57], v[70:73], v[62:65]
	ds_read_b128 v[66:69], v138 offset:192
	ds_read_b128 v[70:73], v138 offset:35008
	s_waitcnt lgkmcnt(1)
	v_mfma_f32_16x16x32_bf16 v[126:129], v[50:53], v[66:69], v[58:61]
	s_waitcnt lgkmcnt(0)
	v_mfma_f32_16x16x32_bf16 v[122:125], v[50:53], v[70:73], v[62:65]
	s_nop 0
	ds_read_b128 v[58:61], v138 offset:4352
	s_nop 0
	ds_read_b128 v[62:65], v138 offset:39168
	ds_read_b128 v[66:69], v138 offset:4416
	ds_read_b128 v[70:73], v138 offset:39232
	v_add_f32_e32 v126, v170, v126
	s_waitcnt lgkmcnt(3)
	v_mfma_f32_16x16x32_bf16 v[58:61], v[110:113], v[58:61], 0
	v_add_f32_e32 v127, v170, v127
	v_mul_f32_e32 v126, 0xbfb8aa3b, v126
	v_mul_f32_e32 v127, 0xbfb8aa3b, v127
	s_waitcnt lgkmcnt(2)
	v_mfma_f32_16x16x32_bf16 v[62:65], v[110:113], v[62:65], 0
	v_exp_f32_e32 v126, v126
	v_exp_f32_e32 v127, v127
	v_add_f32_e32 v122, v174, v122
	s_waitcnt lgkmcnt(1)
	v_mfma_f32_16x16x32_bf16 v[58:61], v[82:85], v[66:69], v[58:61]
	v_add_f32_e32 v126, 1.0, v126
	v_add_f32_e32 v127, 1.0, v127
	v_rcp_f32_e32 v126, v126
	s_waitcnt lgkmcnt(0)
	v_mfma_f32_16x16x32_bf16 v[62:65], v[82:85], v[70:73], v[62:65]
	ds_read_b128 v[66:69], v138 offset:4480
	ds_read_b128 v[70:73], v138 offset:39296
	v_rcp_f32_e32 v127, v127
	v_mul_f32_e32 v126, v176, v126
	s_waitcnt lgkmcnt(1)
	v_mfma_f32_16x16x32_bf16 v[58:61], v[54:57], v[66:69], v[58:61]
	v_add_f32_e32 v123, v174, v123
	v_mul_f32_e32 v127, v176, v127
	v_mul_f32_e32 v122, 0xbfb8aa3b, v122
	s_waitcnt lgkmcnt(0)
	v_mfma_f32_16x16x32_bf16 v[62:65], v[54:57], v[70:73], v[62:65]
	ds_read_b128 v[66:69], v138 offset:4544
	ds_read_b128 v[70:73], v138 offset:39360
	v_mul_f32_e32 v123, 0xbfb8aa3b, v123
	v_exp_f32_e32 v122, v122
	s_waitcnt lgkmcnt(1)
	v_mfma_f32_16x16x32_bf16 v[118:121], v[50:53], v[66:69], v[58:61]
	v_exp_f32_e32 v123, v123
	v_add_f32_e32 v122, 1.0, v122
	v_rcp_f32_e32 v122, v122
	s_waitcnt lgkmcnt(0)
	v_mfma_f32_16x16x32_bf16 v[114:117], v[50:53], v[70:73], v[62:65]
	ds_read_b128 v[58:61], v138 offset:8704
	s_nop 1
	ds_read_b128 v[62:65], v138 offset:43520
	ds_read_b128 v[66:69], v138 offset:8768
	ds_read_b128 v[70:73], v138 offset:43584
	v_add_f32_e32 v123, 1.0, v123
	s_waitcnt lgkmcnt(3)
	v_mfma_f32_16x16x32_bf16 v[58:61], v[110:113], v[58:61], 0
	v_rcp_f32_e32 v123, v123
	v_add_f32_e32 v124, v174, v124
	v_add_f32_e32 v125, v174, v125
	s_waitcnt lgkmcnt(2)
	v_mfma_f32_16x16x32_bf16 v[62:65], v[110:113], v[62:65], 0
	v_mul_f32_e32 v124, 0xbfb8aa3b, v124
	v_mul_f32_e32 v125, 0xbfb8aa3b, v125
	v_exp_f32_e32 v124, v124
	s_waitcnt lgkmcnt(1)
	v_mfma_f32_16x16x32_bf16 v[58:61], v[82:85], v[66:69], v[58:61]
	v_exp_f32_e32 v125, v125
	v_add_f32_e32 v118, v171, v118
	v_add_f32_e32 v119, v171, v119
	s_waitcnt lgkmcnt(0)
	v_mfma_f32_16x16x32_bf16 v[62:65], v[82:85], v[70:73], v[62:65]
	ds_read_b128 v[66:69], v138 offset:8832
	ds_read_b128 v[70:73], v138 offset:43648
	v_add_f32_e32 v124, 1.0, v124
	v_add_f32_e32 v125, 1.0, v125
	s_waitcnt lgkmcnt(1)
	v_mfma_f32_16x16x32_bf16 v[58:61], v[54:57], v[66:69], v[58:61]
	v_mul_f32_e32 v118, 0xbfb8aa3b, v118
	v_mul_f32_e32 v119, 0xbfb8aa3b, v119
	v_rcp_f32_e32 v124, v124
	s_waitcnt lgkmcnt(0)
	v_mfma_f32_16x16x32_bf16 v[62:65], v[54:57], v[70:73], v[62:65]
	ds_read_b128 v[66:69], v138 offset:8896
	ds_read_b128 v[70:73], v138 offset:43712
	v_exp_f32_e32 v118, v118
	v_exp_f32_e32 v119, v119
	s_waitcnt lgkmcnt(1)
	v_mfma_f32_16x16x32_bf16 v[106:109], v[50:53], v[66:69], v[58:61]
	v_add_f32_e32 v118, 1.0, v118
	v_add_f32_e32 v119, 1.0, v119
	v_rcp_f32_e32 v118, v118
	s_waitcnt lgkmcnt(0)
	v_mfma_f32_16x16x32_bf16 v[102:105], v[50:53], v[70:73], v[62:65]
	ds_read_b128 v[58:61], v74
	s_nop 1
	ds_read_b128 v[62:65], v74 offset:34816
	ds_read_b128 v[66:69], v74 offset:64
	ds_read_b128 v[70:73], v74 offset:34880
	v_rcp_f32_e32 v119, v119
	s_waitcnt lgkmcnt(3)
	v_mfma_f32_16x16x32_bf16 v[58:61], v[110:113], v[58:61], 0
	v_add_f32_e32 v114, v175, v114
	v_mul_f32_e32 v118, v177, v118
	v_add_f32_e32 v115, v175, v115
	s_waitcnt lgkmcnt(2)
	v_mfma_f32_16x16x32_bf16 v[62:65], v[110:113], v[62:65], 0
	v_mul_f32_e32 v119, v177, v119
	v_mul_f32_e32 v114, 0xbfb8aa3b, v114
	v_mul_f32_e32 v115, 0xbfb8aa3b, v115
	s_waitcnt lgkmcnt(1)
	v_mfma_f32_16x16x32_bf16 v[58:61], v[82:85], v[66:69], v[58:61]
	v_exp_f32_e32 v114, v114
	v_exp_f32_e32 v115, v115
	v_add_f32_e32 v106, v178, v106
	s_waitcnt lgkmcnt(0)
	v_mfma_f32_16x16x32_bf16 v[62:65], v[82:85], v[70:73], v[62:65]
	ds_read_b128 v[66:69], v74 offset:128
	ds_read_b128 v[70:73], v74 offset:34944
	v_add_f32_e32 v114, 1.0, v114
	v_add_f32_e32 v115, 1.0, v115
	s_waitcnt lgkmcnt(1)
	v_mfma_f32_16x16x32_bf16 v[58:61], v[54:57], v[66:69], v[58:61]
	v_rcp_f32_e32 v114, v114
	v_rcp_f32_e32 v115, v115
	v_add_f32_e32 v107, v178, v107
	s_waitcnt lgkmcnt(0)
	v_mfma_f32_16x16x32_bf16 v[62:65], v[54:57], v[70:73], v[62:65]
	ds_read_b128 v[66:69], v74 offset:192
	ds_read_b128 v[70:73], v74 offset:35008
	v_mul_f32_e32 v106, 0xbfb8aa3b, v106
	v_mul_f32_e32 v107, 0xbfb8aa3b, v107
	s_waitcnt lgkmcnt(1)
	v_mfma_f32_16x16x32_bf16 v[90:93], v[50:53], v[66:69], v[58:61]
	v_exp_f32_e32 v106, v106
	v_exp_f32_e32 v107, v107
	v_add_f32_e32 v102, v180, v102
	s_waitcnt lgkmcnt(0)
	v_mfma_f32_16x16x32_bf16 v[86:89], v[50:53], v[70:73], v[62:65]
	ds_read_b128 v[58:61], v138 offset:17408
	s_nop 1
	ds_read_b128 v[62:65], v138 offset:52224
	ds_read_b128 v[66:69], v138 offset:17472
	ds_read_b128 v[70:73], v138 offset:52288
	v_add_f32_e32 v106, 1.0, v106
	s_waitcnt lgkmcnt(3)
; #define LAS __attribute__((address_space(3)))
; __device__ __forceinline__ float fsig2(float x) { return __builtin_amdgcn_rcpf(1.0f + __builtin_amdgcn_exp2f(-LOG2E * x)); }
; template <int PASS> __device__ __forceinline__ void lru_wave_item(LAS unsigned char* lds, LAS unsigned char* vw, int b, int c, int h, const MixP& p, int lane, float (&Hrun)[8], bool cont) {
;     ...
;             for (int kk = 0; kk < 4; ++kk) af[kk] = *(const LAS bf16x8*)(vw + fr * WROW + kk * 64 + fq * 16);
; #pragma unroll
;             for (int n = 0; n < 8; ++n) {
;                 aR[n] = (f32x4){0.f, 0.f, 0.f, 0.f}; aI[n] = (f32x4){0.f, 0.f, 0.f, 0.f};
; #pragma unroll
;                 for (int kk = 0; kk < 4; ++kk) {
;                     const bf16x8 ba = *(const LAS bf16x8*)(lds + WA_OFF + (16 * n + fr) * WROW + kk * 64 + fq * 16);
;                     const bf16x8 bx = *(const LAS bf16x8*)(lds + WX_OFF + (16 * n + fr) * WROW + kk * 64 + fq * 16);
;                     aR[n] = __builtin_amdgcn_mfma_f32_16x16x32_bf16(af[kk], ba, aR[n], 0, 0, 0);
;                     aI[n] = __builtin_amdgcn_mfma_f32_16x16x32_bf16(af[kk], bx, aI[n], 0, 0, 0);
;                 }
;             }
;         }
; #pragma unroll
;         for (int n = 0; n < 8; ++n) {
;             const f32x4 aVn = __builtin_amdgcn_mfma_f32_16x16x32_bf16(af[n >> 1], idf[n & 1], (f32x4){0.f, 0.f, 0.f, 0.f}, 0, 0, 0);
;             float av[4], bxv[4];
; #pragma unroll
;             for (int j = 0; j < 4; ++j) {
;                 const float r = fsig2(aR[n][j] + pba[n]), ig = fsig2(aI[n][j] + pbx[n]);
;                 const float a = __builtin_amdgcn_exp2f(r * pk8[n]), mult = __builtin_amdgcn_sqrtf(fmaxf(1.0f - a * a, 0.f));
	v_mfma_f32_16x16x32_bf16 v[58:61], v[110:113], v[58:61], 0
	v_add_f32_e32 v107, 1.0, v107
	v_rcp_f32_e32 v106, v106
	v_rcp_f32_e32 v107, v107
	s_waitcnt lgkmcnt(2)
	v_mfma_f32_16x16x32_bf16 v[62:65], v[110:113], v[62:65], 0
	v_add_f32_e32 v103, v180, v103
	v_mul_f32_e32 v106, v182, v106
	v_mul_f32_e32 v107, v182, v107
	s_waitcnt lgkmcnt(1)
	v_mfma_f32_16x16x32_bf16 v[58:61], v[82:85], v[66:69], v[58:61]
	v_mul_f32_e32 v102, 0xbfb8aa3b, v102
	v_mul_f32_e32 v103, 0xbfb8aa3b, v103
	v_exp_f32_e32 v102, v102
	s_waitcnt lgkmcnt(0)
	v_mfma_f32_16x16x32_bf16 v[62:65], v[82:85], v[70:73], v[62:65]
	ds_read_b128 v[66:69], v138 offset:17536
	ds_read_b128 v[70:73], v138 offset:52352
	v_exp_f32_e32 v103, v103
	v_add_f32_e32 v102, 1.0, v102
	s_waitcnt lgkmcnt(1)
	v_mfma_f32_16x16x32_bf16 v[58:61], v[54:57], v[66:69], v[58:61]
	v_add_f32_e32 v103, 1.0, v103
	v_rcp_f32_e32 v102, v102
	v_rcp_f32_e32 v103, v103
	s_waitcnt lgkmcnt(0)
	v_mfma_f32_16x16x32_bf16 v[62:65], v[54:57], v[70:73], v[62:65]
	ds_read_b128 v[66:69], v138 offset:17600
	ds_read_b128 v[70:73], v138 offset:52416
	v_add_f32_e32 v104, v180, v104
	v_add_f32_e32 v105, v180, v105
	s_waitcnt lgkmcnt(1)
	v_mfma_f32_16x16x32_bf16 v[78:81], v[50:53], v[66:69], v[58:61]
	v_mul_f32_e32 v104, 0xbfb8aa3b, v104
	v_mul_f32_e32 v105, 0xbfb8aa3b, v105
	v_exp_f32_e32 v104, v104
	s_waitcnt lgkmcnt(0)
	v_mfma_f32_16x16x32_bf16 v[74:77], v[50:53], v[70:73], v[62:65]
	ds_read_b128 v[58:61], v138 offset:21760
	s_nop 1
	ds_read_b128 v[62:65], v138 offset:56576
	ds_read_b128 v[66:69], v138 offset:21824
	ds_read_b128 v[70:73], v138 offset:56640
	v_exp_f32_e32 v105, v105
	s_waitcnt lgkmcnt(3)
	v_mfma_f32_16x16x32_bf16 v[58:61], v[110:113], v[58:61], 0
	v_add_f32_e32 v104, 1.0, v104
	v_add_f32_e32 v105, 1.0, v105
	v_rcp_f32_e32 v104, v104
	s_waitcnt lgkmcnt(2)
	v_mfma_f32_16x16x32_bf16 v[62:65], v[110:113], v[62:65], 0
	v_add_f32_e32 v90, v179, v90
	v_add_f32_e32 v91, v179, v91
	v_mul_f32_e32 v90, 0xbfb8aa3b, v90
	s_waitcnt lgkmcnt(1)
	v_mfma_f32_16x16x32_bf16 v[58:61], v[82:85], v[66:69], v[58:61]
	v_mul_f32_e32 v91, 0xbfb8aa3b, v91
	v_exp_f32_e32 v90, v90
	v_exp_f32_e32 v91, v91
	s_waitcnt lgkmcnt(0)
	v_mfma_f32_16x16x32_bf16 v[62:65], v[82:85], v[70:73], v[62:65]
	ds_read_b128 v[66:69], v138 offset:21888
	ds_read_b128 v[70:73], v138 offset:56704
	v_add_f32_e32 v90, 1.0, v90
	v_add_f32_e32 v91, 1.0, v91
	s_waitcnt lgkmcnt(1)
	v_mfma_f32_16x16x32_bf16 v[58:61], v[54:57], v[66:69], v[58:61]
	ds_read_b128 v[66:69], v138 offset:21952
	ds_read_b128 v[94:97], v138 offset:56768
	v_rcp_f32_e32 v90, v90
	v_rcp_f32_e32 v91, v91
	s_waitcnt lgkmcnt(2)
	v_mfma_f32_16x16x32_bf16 v[62:65], v[54:57], v[70:73], v[62:65]
	v_add_f32_e32 v86, v181, v86
	v_mul_f32_e32 v90, v183, v90
	v_add_f32_e32 v87, v181, v87
	s_waitcnt lgkmcnt(1)
	v_mfma_f32_16x16x32_bf16 v[70:73], v[50:53], v[66:69], v[58:61]
	v_mul_f32_e32 v91, v183, v91
	v_mul_f32_e32 v86, 0xbfb8aa3b, v86
	v_mul_f32_e32 v87, 0xbfb8aa3b, v87
	s_waitcnt lgkmcnt(0)
	v_mfma_f32_16x16x32_bf16 v[66:69], v[50:53], v[94:97], v[62:65]
	ds_read_b128 v[58:61], v138 offset:26112
	s_nop 1
	ds_read_b128 v[62:65], v138 offset:60928
	ds_read_b128 v[94:97], v138 offset:26176
	ds_read_b128 v[98:101], v138 offset:60992
	v_exp_f32_e32 v86, v86
	s_waitcnt lgkmcnt(3)
	v_mfma_f32_16x16x32_bf16 v[58:61], v[110:113], v[58:61], 0
	v_exp_f32_e32 v87, v87
	v_add_f32_e32 v86, 1.0, v86
	v_rcp_f32_e32 v86, v86
	s_waitcnt lgkmcnt(2)
	v_mfma_f32_16x16x32_bf16 v[62:65], v[110:113], v[62:65], 0
	v_add_f32_e32 v87, 1.0, v87
	v_rcp_f32_e32 v87, v87
	v_add_f32_e32 v78, v184, v78
	s_waitcnt lgkmcnt(1)
	v_mfma_f32_16x16x32_bf16 v[58:61], v[82:85], v[94:97], v[58:61]
	v_add_f32_e32 v79, v184, v79
	v_mul_f32_e32 v78, 0xbfb8aa3b, v78
	v_mul_f32_e32 v79, 0xbfb8aa3b, v79
	s_waitcnt lgkmcnt(0)
	v_mfma_f32_16x16x32_bf16 v[62:65], v[82:85], v[98:101], v[62:65]
	ds_read_b128 v[94:97], v138 offset:26240
	ds_read_b128 v[98:101], v138 offset:61056
	v_exp_f32_e32 v78, v78
	v_exp_f32_e32 v79, v79
	s_waitcnt lgkmcnt(1)
	v_mfma_f32_16x16x32_bf16 v[58:61], v[54:57], v[94:97], v[58:61]
	v_add_f32_e32 v78, 1.0, v78
	v_add_f32_e32 v79, 1.0, v79
	v_rcp_f32_e32 v78, v78
	s_waitcnt lgkmcnt(0)
	v_mfma_f32_16x16x32_bf16 v[94:97], v[54:57], v[98:101], v[62:65]
	s_nop 2
	ds_read_b128 v[62:65], v138 offset:26304
	ds_read_b128 v[98:101], v138 offset:61120
	v_rcp_f32_e32 v79, v79
	v_add_f32_e32 v74, v186, v74
	s_waitcnt lgkmcnt(1)
	v_mfma_f32_16x16x32_bf16 v[62:65], v[50:53], v[62:65], v[58:61]
	v_mul_f32_e32 v78, v188, v78
	v_add_f32_e32 v75, v186, v75
	v_mul_f32_e32 v79, v188, v79
	s_waitcnt lgkmcnt(0)
	v_mfma_f32_16x16x32_bf16 v[58:61], v[50:53], v[98:101], v[94:97]
	v_mul_f32_e32 v74, 0xbfb8aa3b, v74
	v_mul_f32_e32 v75, 0xbfb8aa3b, v75
	v_exp_f32_e32 v74, v74
	v_add_u32_e32 v94, v234, v236
	ds_read_b128 v[96:99], v94
	ds_read_b128 v[198:201], v94 offset:34816
	ds_read_b128 v[202:205], v94 offset:64
	ds_read_b128 v[138:141], v94 offset:34880
	s_waitcnt lgkmcnt(3)
	v_mfma_f32_16x16x32_bf16 v[96:99], v[110:113], v[96:99], 0
	v_exp_f32_e32 v75, v75
	v_add_f32_e32 v74, 1.0, v74
	v_rcp_f32_e32 v74, v74
	s_waitcnt lgkmcnt(2)
	v_mfma_f32_16x16x32_bf16 v[198:201], v[110:113], v[198:201], 0
	v_add_f32_e32 v75, 1.0, v75
	v_rcp_f32_e32 v75, v75
	v_add_f32_e32 v76, v186, v76
	s_waitcnt lgkmcnt(1)
	v_mfma_f32_16x16x32_bf16 v[96:99], v[82:85], v[202:205], v[96:99]
	v_add_f32_e32 v77, v186, v77
	v_mul_f32_e32 v76, 0xbfb8aa3b, v76
	v_mul_f32_e32 v77, 0xbfb8aa3b, v77
	s_waitcnt lgkmcnt(0)
	v_mfma_f32_16x16x32_bf16 v[138:141], v[82:85], v[138:141], v[198:201]
	s_nop 2
	ds_read_b128 v[198:201], v94 offset:128
	ds_read_b128 v[202:205], v94 offset:34944
	v_exp_f32_e32 v76, v76
	v_exp_f32_e32 v77, v77
	s_waitcnt lgkmcnt(1)
; __device__ __forceinline__ float fsig2(float x) { return __builtin_amdgcn_rcpf(1.0f + __builtin_amdgcn_exp2f(-LOG2E * x)); }
; template <int PASS> __device__ __forceinline__ void lru_wave_item(LAS unsigned char* lds, LAS unsigned char* vw, int b, int c, int h, const MixP& p, int lane, float (&Hrun)[8], bool cont) {
;     ...
;         for (int n = 0; n < 8; ++n) {
;             const f32x4 aVn = __builtin_amdgcn_mfma_f32_16x16x32_bf16(af[n >> 1], idf[n & 1], (f32x4){0.f, 0.f, 0.f, 0.f}, 0, 0, 0);
;             float av[4], bxv[4];
; #pragma unroll
;             for (int j = 0; j < 4; ++j) {
;                 const float r = fsig2(aR[n][j] + pba[n]), ig = fsig2(aI[n][j] + pbx[n]);
;                 const float a = __builtin_amdgcn_exp2f(r * pk8[n]), mult = __builtin_amdgcn_sqrtf(fmaxf(1.0f - a * a, 0.f));
;                 av[j] = a; bxv[j] = mult * ig * aVn[j];
;             }
;             const float H0 = bxv[0], H1 = av[1] * H0 + bxv[1], H2 = av[2] * H1 + bxv[2], H3 = av[3] * H2 + bxv[3];
;             const float A0 = av[0], A1 = av[1] * A0, A2 = av[2] * A1, A3 = av[3] * A2;
;             float At[4], Ht[4];
; #pragma unroll
;             for (int q = 0; q < 4; ++q) { At[q] = __shfl(A3, fr + 16 * q); Ht[q] = __shfl(H3, fr + 16 * q); }
;             const float c0 = Hrun[n], c1 = At[0] * c0 + Ht[0], c2 = At[1] * c1 + Ht[1], c3 = At[2] * c2 + Ht[2], c4 = At[3] * c3 + Ht[3];
;             Hrun[n] = c4;
;             if (PASS == 1) Arun[n] *= (At[0] * At[1]) * (At[2] * At[3]);
	v_mfma_f32_16x16x32_bf16 v[96:99], v[54:57], v[198:201], v[96:99]
	v_add_f32_e32 v76, 1.0, v76
	v_add_f32_e32 v77, 1.0, v77
	v_rcp_f32_e32 v76, v76
	s_waitcnt lgkmcnt(0)
	v_mfma_f32_16x16x32_bf16 v[138:141], v[54:57], v[202:205], v[138:141]
	ds_read_b128 v[198:201], v94 offset:192
	ds_read_b128 v[202:205], v94 offset:35008
	v_add_f32_e32 v70, v185, v70
	v_add_f32_e32 v71, v185, v71
	s_waitcnt lgkmcnt(1)
	v_mfma_f32_16x16x32_bf16 v[98:101], v[50:53], v[198:201], v[96:99]
	v_exp_f32_e32 v198, v126
	v_exp_f32_e32 v199, v127
	v_mul_f32_e32 v70, 0xbfb8aa3b, v70
	s_waitcnt lgkmcnt(0)
	v_mfma_f32_16x16x32_bf16 v[94:97], v[50:53], v[202:205], v[138:141]
	v_fma_f32 v126, -v198, v198, 1.0
	v_fma_f32 v127, -v199, v199, 1.0
	v_max_f32_e32 v126, 0, v126
	v_max_f32_e32 v127, 0, v127
	v_sqrt_f32_e32 v126, v126
	v_sqrt_f32_e32 v127, v127
	v_and_or_b32 v138, v213, 64, v137
	v_lshlrev_b32_e32 v151, 2, v138
	v_mfma_f32_16x16x32_bf16 v[138:141], v[110:113], v[2:5], 0
	v_mul_f32_e64 v122, v122, v126
	v_mul_f32_e64 v123, v123, v127
	v_add_f32_e32 v126, v170, v128
	v_mul_f32_e32 v126, 0xbfb8aa3b, v126
	v_exp_f32_e32 v126, v126
	v_rcp_f32_e32 v128, v125
	s_nop 1
	v_pk_mul_f32 v[122:123], v[122:123], v[138:139]
	v_mfma_f32_16x16x32_bf16 v[110:113], v[110:113], v[6:9], 0
	v_add_f32_e32 v126, 1.0, v126
	v_rcp_f32_e32 v126, v126
	v_fmac_f32_e32 v123, v199, v122
	v_mul_f32_e32 v71, 0xbfb8aa3b, v71
	v_exp_f32_e32 v70, v70
	v_mul_f32_e32 v126, v176, v126
	v_exp_f32_e32 v127, v126
	v_add_f32_e32 v126, v170, v129
	v_mul_f32_e32 v126, 0xbfb8aa3b, v126
	v_exp_f32_e32 v126, v126
	v_fma_f32 v122, -v127, v127, 1.0
	v_max_f32_e32 v122, 0, v122
	v_exp_f32_e32 v71, v71
	v_add_f32_e32 v126, 1.0, v126
	v_rcp_f32_e32 v126, v126
	v_add_f32_e32 v70, 1.0, v70
	v_add_f32_e32 v71, 1.0, v71
	v_rcp_f32_e32 v70, v70
	v_mul_f32_e32 v125, v176, v126
	v_sqrt_f32_e32 v126, v122
	v_exp_f32_e32 v139, v125
	v_mov_b32_e32 v125, v123
	v_rcp_f32_e32 v71, v71
	v_pk_mul_f32 v[122:123], v[124:125], v[126:127]
	v_exp_f32_e32 v124, v119
	v_fmac_f32_e32 v123, v122, v140
	v_fma_f32 v122, -v139, v139, 1.0
	v_max_f32_e32 v122, 0, v122
	v_sqrt_f32_e32 v138, v122
	v_mul_f32_e32 v122, v199, v198
	v_mul_f32_e32 v122, v127, v122
	v_mul_f32_e32 v122, v139, v122
	v_mov_b32_e32 v129, v123
	ds_bpermute_b32 v123, v151, v122
	ds_bpermute_b32 v127, v151, v122 offset:64
	ds_bpermute_b32 v199, v151, v122 offset:128
	ds_bpermute_b32 v203, v151, v122 offset:192
	v_exp_f32_e32 v122, v118
	v_fma_f32 v119, -v124, v124, 1.0
	v_max_f32_e32 v119, 0, v119
	v_sqrt_f32_e32 v119, v119
	v_fma_f32 v118, -v122, v122, 1.0
	v_max_f32_e32 v118, 0, v118
	v_sqrt_f32_e32 v118, v118
	v_pk_mul_f32 v[204:205], v[128:129], v[138:139]
	v_add_f32_e32 v66, v187, v66
	v_fmac_f32_e32 v205, v204, v141
	v_pk_mul_f32 v[114:115], v[114:115], v[118:119]
	ds_bpermute_b32 v125, v151, v205
	v_pk_mul_f32 v[110:111], v[114:115], v[110:111]
	v_add_f32_e32 v114, v171, v120
	v_mul_f32_e32 v114, 0xbfb8aa3b, v114
	v_exp_f32_e32 v114, v114
	v_fmac_f32_e32 v111, v124, v110
	ds_bpermute_b32 v129, v151, v205 offset:64
	ds_bpermute_b32 v201, v151, v205 offset:128
	v_add_f32_e32 v114, 1.0, v114
	v_rcp_f32_e32 v115, v114
	v_add_f32_e32 v114, v175, v116
	v_mul_f32_e32 v114, 0xbfb8aa3b, v114
	v_exp_f32_e32 v114, v114
	v_mul_f32_e32 v115, v177, v115
	v_exp_f32_e32 v119, v115
	v_add_f32_e32 v115, v171, v121
	v_mul_f32_e32 v115, 0xbfb8aa3b, v115
	v_exp_f32_e32 v115, v115
	v_fma_f32 v110, -v119, v119, 1.0
	v_add_f32_e32 v114, 1.0, v114
	v_max_f32_e32 v110, 0, v110
	v_add_f32_e32 v115, 1.0, v115
	v_rcp_f32_e32 v115, v115
	v_rcp_f32_e32 v114, v114
	v_sqrt_f32_e32 v118, v110
	v_add_f32_e32 v116, v175, v117
	v_mul_f32_e32 v115, v177, v115
	v_exp_f32_e32 v121, v115
	v_mov_b32_e32 v115, v111
	v_pk_mul_f32 v[110:111], v[114:115], v[118:119]
	v_exp_f32_e32 v114, v106
	v_exp_f32_e32 v115, v107
	v_mul_f32_e32 v116, 0xbfb8aa3b, v116
	v_exp_f32_e32 v116, v116
	v_fma_f32 v106, -v114, v114, 1.0
	v_fma_f32 v107, -v115, v115, 1.0
	v_max_f32_e32 v106, 0, v106
	v_max_f32_e32 v107, 0, v107
	v_sqrt_f32_e32 v106, v106
	v_sqrt_f32_e32 v107, v107
	v_fmac_f32_e32 v111, v110, v112
	v_fma_f32 v110, -v121, v121, 1.0
	v_add_f32_e32 v116, 1.0, v116
	v_max_f32_e32 v110, 0, v110
	v_rcp_f32_e32 v116, v116
	v_sqrt_f32_e32 v120, v110
	v_pk_mul_f32 v[102:103], v[102:103], v[106:107]
	v_add_f32_e32 v106, v178, v108
	v_mul_f32_e32 v106, 0xbfb8aa3b, v106
	v_mov_b32_e32 v117, v111
	v_exp_f32_e32 v106, v106
	v_pk_mul_f32 v[110:111], v[116:117], v[120:121]
	ds_bpermute_b32 v205, v151, v205 offset:192
	v_fmac_f32_e32 v111, v110, v113
	v_mul_f32_e32 v110, v124, v122
	v_mul_f32_e32 v110, v119, v110
	v_mul_f32_e32 v110, v121, v110
	v_add_f32_e32 v106, 1.0, v106
	ds_bpermute_b32 v122, v151, v110
	ds_bpermute_b32 v126, v151, v110 offset:64
	ds_bpermute_b32 v198, v151, v110 offset:128
	ds_bpermute_b32 v202, v151, v110 offset:192
	v_rcp_f32_e32 v106, v106
	ds_bpermute_b32 v124, v151, v111
	ds_bpermute_b32 v128, v151, v111 offset:64
	ds_bpermute_b32 v200, v151, v111 offset:128
	ds_bpermute_b32 v204, v151, v111 offset:192
	v_mul_f32_e32 v106, v182, v106
	s_waitcnt lgkmcnt(6)
	v_pk_mul_f32 v[110:111], v[122:123], v[126:127]
	s_waitcnt lgkmcnt(4)
	v_pk_mul_f32 v[112:113], v[198:199], v[202:203]
	v_exp_f32_e32 v107, v106
	v_add_f32_e32 v106, v178, v109
	v_pk_mul_f32 v[110:111], v[110:111], v[112:113]
	s_waitcnt lgkmcnt(3)
	v_pk_fma_f32 v[112:113], v[172:173], v[122:123], v[124:125]
	v_mul_f32_e32 v106, 0xbfb8aa3b, v106
	s_waitcnt lgkmcnt(2)
	v_pk_fma_f32 v[112:113], v[112:113], v[126:127], v[128:129]
	v_exp_f32_e32 v106, v106
	s_waitcnt lgkmcnt(1)
	v_pk_fma_f32 v[112:113], v[112:113], v[198:199], v[200:201]
	v_pk_mul_f32 v[162:163], v[162:163], v[110:111]
	s_waitcnt lgkmcnt(0)
; __device__ __forceinline__ float fsig2(float x) { return __builtin_amdgcn_rcpf(1.0f + __builtin_amdgcn_exp2f(-LOG2E * x)); }
; template <int PASS> __device__ __forceinline__ void lru_wave_item(LAS unsigned char* lds, LAS unsigned char* vw, int b, int c, int h, const MixP& p, int lane, float (&Hrun)[8], bool cont) {
;     ...
;         for (int n = 0; n < 8; ++n) {
;             const f32x4 aVn = __builtin_amdgcn_mfma_f32_16x16x32_bf16(af[n >> 1], idf[n & 1], (f32x4){0.f, 0.f, 0.f, 0.f}, 0, 0, 0);
;             float av[4], bxv[4];
; #pragma unroll
;             for (int j = 0; j < 4; ++j) {
;                 const float r = fsig2(aR[n][j] + pba[n]), ig = fsig2(aI[n][j] + pbx[n]);
;                 const float a = __builtin_amdgcn_exp2f(r * pk8[n]), mult = __builtin_amdgcn_sqrtf(fmaxf(1.0f - a * a, 0.f));
;                 av[j] = a; bxv[j] = mult * ig * aVn[j];
;             }
;             const float H0 = bxv[0], H1 = av[1] * H0 + bxv[1], H2 = av[2] * H1 + bxv[2], H3 = av[3] * H2 + bxv[3];
;             const float A0 = av[0], A1 = av[1] * A0, A2 = av[2] * A1, A3 = av[3] * A2;
;             float At[4], Ht[4];
; #pragma unroll
;             for (int q = 0; q < 4; ++q) { At[q] = __shfl(A3, fr + 16 * q); Ht[q] = __shfl(H3, fr + 16 * q); }
;             const float c0 = Hrun[n], c1 = At[0] * c0 + Ht[0], c2 = At[1] * c1 + Ht[1], c3 = At[2] * c2 + Ht[2], c4 = At[3] * c3 + Ht[3];
;             Hrun[n] = c4;
;             if (PASS == 1) Arun[n] *= (At[0] * At[1]) * (At[2] * At[3]);
	v_pk_fma_f32 v[172:173], v[112:113], v[202:203], v[204:205]
	v_mfma_f32_16x16x32_bf16 v[110:113], v[82:85], v[2:5], 0
	v_add_f32_e32 v106, 1.0, v106
	v_rcp_f32_e32 v106, v106
	v_rcp_f32_e32 v108, v105
	v_mfma_f32_16x16x32_bf16 v[82:85], v[82:85], v[6:9], 0
	v_mul_f32_e32 v70, v189, v70
	s_nop 2
	v_pk_mul_f32 v[102:103], v[102:103], v[110:111]
	v_mul_f32_e32 v105, v182, v106
	v_fmac_f32_e32 v103, v115, v102
	v_fma_f32 v102, -v107, v107, 1.0
	v_max_f32_e32 v102, 0, v102
	v_sqrt_f32_e32 v106, v102
	v_exp_f32_e32 v111, v105
	v_mov_b32_e32 v105, v103
	v_add_f32_e32 v67, v187, v67
	v_pk_mul_f32 v[102:103], v[104:105], v[106:107]
	v_mul_f32_e32 v71, v189, v71
	v_fmac_f32_e32 v103, v102, v112
	v_fma_f32 v102, -v111, v111, 1.0
	v_max_f32_e32 v102, 0, v102
	v_sqrt_f32_e32 v110, v102
	v_mov_b32_e32 v109, v103
	v_mul_f32_e32 v66, 0xbfb8aa3b, v66
	v_mul_f32_e32 v67, 0xbfb8aa3b, v67
	v_pk_mul_f32 v[102:103], v[108:109], v[110:111]
	v_exp_f32_e32 v66, v66
	v_fmac_f32_e32 v103, v102, v113
	v_mul_f32_e32 v102, v115, v114
	v_mul_f32_e32 v102, v107, v102
	v_mul_f32_e32 v105, v111, v102
	ds_bpermute_b32 v102, v151, v105
	ds_bpermute_b32 v104, v151, v103
	ds_bpermute_b32 v106, v151, v105 offset:64
	ds_bpermute_b32 v108, v151, v103 offset:64
	ds_bpermute_b32 v110, v151, v105 offset:128
	ds_bpermute_b32 v112, v151, v103 offset:128
	ds_bpermute_b32 v114, v151, v105 offset:192
	ds_bpermute_b32 v116, v151, v103 offset:192
	v_exp_f32_e32 v103, v90
	v_exp_f32_e32 v105, v91
	v_exp_f32_e32 v67, v67
	v_add_f32_e32 v66, 1.0, v66
	v_fma_f32 v90, -v103, v103, 1.0
	v_fma_f32 v91, -v105, v105, 1.0
	v_max_f32_e32 v90, 0, v90
	v_max_f32_e32 v91, 0, v91
	v_sqrt_f32_e32 v90, v90
	v_sqrt_f32_e32 v91, v91
	v_add_f32_e32 v67, 1.0, v67
	v_rcp_f32_e32 v66, v66
	v_rcp_f32_e32 v67, v67
	v_pk_mul_f32 v[86:87], v[86:87], v[90:91]
	v_add_f32_e32 v62, v190, v62
	v_pk_mul_f32 v[82:83], v[86:87], v[82:83]
	v_add_f32_e32 v86, v179, v92
	v_mul_f32_e32 v86, 0xbfb8aa3b, v86
	v_exp_f32_e32 v86, v86
	v_fmac_f32_e32 v83, v105, v82
	v_add_f32_e32 v63, v190, v63
	v_mul_f32_e32 v62, 0xbfb8aa3b, v62
	v_add_f32_e32 v86, 1.0, v86
	v_rcp_f32_e32 v87, v86
	v_add_f32_e32 v86, v181, v88
	v_mul_f32_e32 v86, 0xbfb8aa3b, v86
	v_exp_f32_e32 v86, v86
	v_mul_f32_e32 v87, v183, v87
	v_exp_f32_e32 v91, v87
	v_add_f32_e32 v87, v179, v93
	v_mul_f32_e32 v87, 0xbfb8aa3b, v87
	v_exp_f32_e32 v87, v87
	v_fma_f32 v82, -v91, v91, 1.0
	v_add_f32_e32 v86, 1.0, v86
	v_max_f32_e32 v82, 0, v82
	v_add_f32_e32 v87, 1.0, v87
	v_rcp_f32_e32 v87, v87
	v_rcp_f32_e32 v86, v86
	v_sqrt_f32_e32 v90, v82
	v_add_f32_e32 v88, v181, v89
	v_mul_f32_e32 v87, v183, v87
	v_exp_f32_e32 v93, v87
	v_mov_b32_e32 v87, v83
	v_pk_mul_f32 v[82:83], v[86:87], v[90:91]
	v_exp_f32_e32 v86, v78
	v_exp_f32_e32 v87, v79
	v_mul_f32_e32 v88, 0xbfb8aa3b, v88
	v_exp_f32_e32 v88, v88
	v_fma_f32 v78, -v86, v86, 1.0
	v_fma_f32 v79, -v87, v87, 1.0
	v_max_f32_e32 v78, 0, v78
	v_max_f32_e32 v79, 0, v79
	v_sqrt_f32_e32 v78, v78
	v_sqrt_f32_e32 v79, v79
	v_fmac_f32_e32 v83, v82, v84
	v_fma_f32 v82, -v93, v93, 1.0
	v_add_f32_e32 v88, 1.0, v88
	v_max_f32_e32 v82, 0, v82
	v_rcp_f32_e32 v88, v88
	v_sqrt_f32_e32 v92, v82
	v_pk_mul_f32 v[74:75], v[74:75], v[78:79]
	v_add_f32_e32 v78, v184, v80
	v_mul_f32_e32 v78, 0xbfb8aa3b, v78
	v_mov_b32_e32 v89, v83
	v_exp_f32_e32 v78, v78
	v_pk_mul_f32 v[82:83], v[88:89], v[92:93]
	v_rcp_f32_e32 v80, v77
	v_fmac_f32_e32 v83, v82, v85
	v_mul_f32_e32 v82, v105, v103
	v_mul_f32_e32 v82, v91, v82
	v_mul_f32_e32 v82, v93, v82
	v_add_f32_e32 v78, 1.0, v78
	ds_bpermute_b32 v103, v151, v82
	ds_bpermute_b32 v107, v151, v82 offset:64
	ds_bpermute_b32 v111, v151, v82 offset:128
	ds_bpermute_b32 v115, v151, v82 offset:192
	v_rcp_f32_e32 v78, v78
	ds_bpermute_b32 v105, v151, v83
	ds_bpermute_b32 v109, v151, v83 offset:64
	ds_bpermute_b32 v113, v151, v83 offset:128
	ds_bpermute_b32 v117, v151, v83 offset:192
	v_mul_f32_e32 v78, v188, v78
	s_waitcnt lgkmcnt(6)
	v_pk_mul_f32 v[82:83], v[102:103], v[106:107]
	s_waitcnt lgkmcnt(4)
	v_pk_mul_f32 v[84:85], v[110:111], v[114:115]
	v_exp_f32_e32 v79, v78
	v_add_f32_e32 v78, v184, v81
	v_pk_mul_f32 v[82:83], v[82:83], v[84:85]
	s_waitcnt lgkmcnt(3)
	v_pk_fma_f32 v[84:85], v[166:167], v[102:103], v[104:105]
	v_mul_f32_e32 v78, 0xbfb8aa3b, v78
	s_waitcnt lgkmcnt(2)
	v_pk_fma_f32 v[84:85], v[84:85], v[106:107], v[108:109]
	v_exp_f32_e32 v78, v78
	s_waitcnt lgkmcnt(1)
	v_pk_fma_f32 v[84:85], v[84:85], v[110:111], v[112:113]
	v_pk_mul_f32 v[168:169], v[168:169], v[82:83]
	s_waitcnt lgkmcnt(0)
; __device__ __forceinline__ float fsig2(float x) { return __builtin_amdgcn_rcpf(1.0f + __builtin_amdgcn_exp2f(-LOG2E * x)); }
; template <int PASS> __device__ __forceinline__ void lru_wave_item(LAS unsigned char* lds, LAS unsigned char* vw, int b, int c, int h, const MixP& p, int lane, float (&Hrun)[8], bool cont) {
;     ...
;         for (int n = 0; n < 8; ++n) {
;             const f32x4 aVn = __builtin_amdgcn_mfma_f32_16x16x32_bf16(af[n >> 1], idf[n & 1], (f32x4){0.f, 0.f, 0.f, 0.f}, 0, 0, 0);
;             float av[4], bxv[4];
; #pragma unroll
;             for (int j = 0; j < 4; ++j) {
;                 const float r = fsig2(aR[n][j] + pba[n]), ig = fsig2(aI[n][j] + pbx[n]);
;                 const float a = __builtin_amdgcn_exp2f(r * pk8[n]), mult = __builtin_amdgcn_sqrtf(fmaxf(1.0f - a * a, 0.f));
;                 av[j] = a; bxv[j] = mult * ig * aVn[j];
;             }
;             const float H0 = bxv[0], H1 = av[1] * H0 + bxv[1], H2 = av[2] * H1 + bxv[2], H3 = av[3] * H2 + bxv[3];
;             const float A0 = av[0], A1 = av[1] * A0, A2 = av[2] * A1, A3 = av[3] * A2;
;             float At[4], Ht[4];
; #pragma unroll
;             for (int q = 0; q < 4; ++q) { At[q] = __shfl(A3, fr + 16 * q); Ht[q] = __shfl(H3, fr + 16 * q); }
;             const float c0 = Hrun[n], c1 = At[0] * c0 + Ht[0], c2 = At[1] * c1 + Ht[1], c3 = At[2] * c2 + Ht[2], c4 = At[3] * c3 + Ht[3];
;             Hrun[n] = c4;
;             if (PASS == 1) Arun[n] *= (At[0] * At[1]) * (At[2] * At[3]);
	v_pk_fma_f32 v[166:167], v[84:85], v[114:115], v[116:117]
	v_mfma_f32_16x16x32_bf16 v[82:85], v[54:57], v[2:5], 0
	v_add_f32_e32 v78, 1.0, v78
	v_rcp_f32_e32 v78, v78
	v_mul_f32_e32 v63, 0xbfb8aa3b, v63
	v_mfma_f32_16x16x32_bf16 v[54:57], v[54:57], v[6:9], 0
	v_exp_f32_e32 v62, v62
	s_nop 2
	v_pk_mul_f32 v[74:75], v[74:75], v[82:83]
	v_mul_f32_e32 v77, v188, v78
	v_fmac_f32_e32 v75, v87, v74
	v_fma_f32 v74, -v79, v79, 1.0
	v_max_f32_e32 v74, 0, v74
	v_sqrt_f32_e32 v78, v74
	v_exp_f32_e32 v83, v77
	v_mov_b32_e32 v77, v75
	v_exp_f32_e32 v63, v63
	v_pk_mul_f32 v[74:75], v[76:77], v[78:79]
	v_add_f32_e32 v62, 1.0, v62
	v_fmac_f32_e32 v75, v74, v84
	v_fma_f32 v74, -v83, v83, 1.0
	v_max_f32_e32 v74, 0, v74
	v_sqrt_f32_e32 v82, v74
	v_mov_b32_e32 v81, v75
	v_add_f32_e32 v63, 1.0, v63
	v_rcp_f32_e32 v62, v62
	v_pk_mul_f32 v[74:75], v[80:81], v[82:83]
	v_rcp_f32_e32 v63, v63
	v_fmac_f32_e32 v75, v74, v85
	v_mul_f32_e32 v74, v87, v86
	v_mul_f32_e32 v74, v79, v74
	v_mul_f32_e32 v77, v83, v74
	ds_bpermute_b32 v74, v151, v77
	ds_bpermute_b32 v76, v151, v75
	ds_bpermute_b32 v78, v151, v77 offset:64
	ds_bpermute_b32 v80, v151, v75 offset:64
	ds_bpermute_b32 v82, v151, v77 offset:128
	ds_bpermute_b32 v84, v151, v75 offset:128
	ds_bpermute_b32 v86, v151, v77 offset:192
	ds_bpermute_b32 v88, v151, v75 offset:192
	v_exp_f32_e32 v75, v70
	v_exp_f32_e32 v77, v71
	v_add_f32_e32 v58, v192, v58
	v_mul_f32_e32 v62, v194, v62
	v_fma_f32 v70, -v75, v75, 1.0
	v_fma_f32 v71, -v77, v77, 1.0
	v_max_f32_e32 v70, 0, v70
	v_max_f32_e32 v71, 0, v71
	v_sqrt_f32_e32 v70, v70
	v_sqrt_f32_e32 v71, v71
	v_add_f32_e32 v59, v192, v59
	v_mul_f32_e32 v63, v194, v63
	v_mul_f32_e32 v58, 0xbfb8aa3b, v58
	v_pk_mul_f32 v[66:67], v[66:67], v[70:71]
	v_mul_f32_e32 v59, 0xbfb8aa3b, v59
	v_pk_mul_f32 v[54:55], v[66:67], v[54:55]
	v_add_f32_e32 v66, v185, v72
	v_mul_f32_e32 v66, 0xbfb8aa3b, v66
	v_exp_f32_e32 v66, v66
	v_fmac_f32_e32 v55, v77, v54
	v_exp_f32_e32 v58, v58
	v_exp_f32_e32 v59, v59
	v_add_f32_e32 v66, 1.0, v66
	v_rcp_f32_e32 v67, v66
	v_add_f32_e32 v66, v187, v68
	v_mul_f32_e32 v66, 0xbfb8aa3b, v66
	v_exp_f32_e32 v66, v66
	v_mul_f32_e32 v67, v189, v67
	v_exp_f32_e32 v71, v67
	v_add_f32_e32 v67, v185, v73
	v_mul_f32_e32 v67, 0xbfb8aa3b, v67
	v_exp_f32_e32 v67, v67
	v_fma_f32 v54, -v71, v71, 1.0
	v_add_f32_e32 v66, 1.0, v66
	v_max_f32_e32 v54, 0, v54
	v_add_f32_e32 v67, 1.0, v67
	v_rcp_f32_e32 v67, v67
	v_rcp_f32_e32 v66, v66
	v_add_f32_e32 v68, v187, v69
	v_sqrt_f32_e32 v70, v54
	v_mul_f32_e32 v67, v189, v67
	v_mul_f32_e32 v68, 0xbfb8aa3b, v68
	v_exp_f32_e32 v73, v67
	v_exp_f32_e32 v68, v68
	v_mov_b32_e32 v67, v55
	v_pk_mul_f32 v[54:55], v[66:67], v[70:71]
	v_exp_f32_e32 v66, v62
	v_fmac_f32_e32 v55, v54, v56
	v_fma_f32 v54, -v73, v73, 1.0
	v_add_f32_e32 v68, 1.0, v68
	v_max_f32_e32 v54, 0, v54
	v_rcp_f32_e32 v68, v68
	v_sqrt_f32_e32 v72, v54
	v_mov_b32_e32 v69, v55
	v_exp_f32_e32 v67, v63
	v_fma_f32 v62, -v66, v66, 1.0
	v_pk_mul_f32 v[54:55], v[68:69], v[72:73]
	v_add_f32_e32 v58, 1.0, v58
	v_fmac_f32_e32 v55, v54, v57
	v_mul_f32_e32 v54, v77, v75
	v_mul_f32_e32 v54, v71, v54
	v_mul_f32_e32 v54, v73, v54
	ds_bpermute_b32 v75, v151, v54
	ds_bpermute_b32 v79, v151, v54 offset:64
	ds_bpermute_b32 v83, v151, v54 offset:128
	ds_bpermute_b32 v87, v151, v54 offset:192
	ds_bpermute_b32 v77, v151, v55
	ds_bpermute_b32 v81, v151, v55 offset:64
	ds_bpermute_b32 v85, v151, v55 offset:128
	ds_bpermute_b32 v89, v151, v55 offset:192
	s_waitcnt lgkmcnt(6)
	v_pk_mul_f32 v[54:55], v[74:75], v[78:79]
	s_waitcnt lgkmcnt(4)
	v_pk_mul_f32 v[56:57], v[82:83], v[86:87]
	v_fma_f32 v63, -v67, v67, 1.0
	v_pk_mul_f32 v[54:55], v[54:55], v[56:57]
	s_waitcnt lgkmcnt(3)
	v_pk_fma_f32 v[56:57], v[160:161], v[74:75], v[76:77]
	v_max_f32_e32 v62, 0, v62
	s_waitcnt lgkmcnt(2)
	v_pk_fma_f32 v[56:57], v[56:57], v[78:79], v[80:81]
	v_add_f32_e32 v59, 1.0, v59
	v_max_f32_e32 v63, 0, v63
	s_waitcnt lgkmcnt(1)
	v_pk_fma_f32 v[56:57], v[56:57], v[82:83], v[84:85]
	v_rcp_f32_e32 v58, v58
	v_sqrt_f32_e32 v62, v62
	v_rcp_f32_e32 v59, v59
	v_sqrt_f32_e32 v63, v63
	s_waitcnt lgkmcnt(0)
; __device__ __forceinline__ float fsig2(float x) { return __builtin_amdgcn_rcpf(1.0f + __builtin_amdgcn_exp2f(-LOG2E * x)); }
; template <int PASS> __device__ __forceinline__ void lru_wave_item(LAS unsigned char* lds, LAS unsigned char* vw, int b, int c, int h, const MixP& p, int lane, float (&Hrun)[8], bool cont) {
;     ...
;         for (int n = 0; n < 8; ++n) {
;             const f32x4 aVn = __builtin_amdgcn_mfma_f32_16x16x32_bf16(af[n >> 1], idf[n & 1], (f32x4){0.f, 0.f, 0.f, 0.f}, 0, 0, 0);
;             float av[4], bxv[4];
; #pragma unroll
;             for (int j = 0; j < 4; ++j) {
;                 const float r = fsig2(aR[n][j] + pba[n]), ig = fsig2(aI[n][j] + pbx[n]);
;                 const float a = __builtin_amdgcn_exp2f(r * pk8[n]), mult = __builtin_amdgcn_sqrtf(fmaxf(1.0f - a * a, 0.f));
;                 av[j] = a; bxv[j] = mult * ig * aVn[j];
;             }
;             const float H0 = bxv[0], H1 = av[1] * H0 + bxv[1], H2 = av[2] * H1 + bxv[2], H3 = av[3] * H2 + bxv[3];
;             const float A0 = av[0], A1 = av[1] * A0, A2 = av[2] * A1, A3 = av[3] * A2;
;             float At[4], Ht[4];
; #pragma unroll
;             for (int q = 0; q < 4; ++q) { At[q] = __shfl(A3, fr + 16 * q); Ht[q] = __shfl(H3, fr + 16 * q); }
;             const float c0 = Hrun[n], c1 = At[0] * c0 + Ht[0], c2 = At[1] * c1 + Ht[1], c3 = At[2] * c2 + Ht[2], c4 = At[3] * c3 + Ht[3];
;             Hrun[n] = c4;
;             if (PASS == 1) Arun[n] *= (At[0] * At[1]) * (At[2] * At[3]);
;     ...
;     if (PASS == 1 && fq == 0) {
; #pragma unroll
;         for (int n = 0; n < 8; ++n) *(f32x2*)(p.summ + (((size_t)b * NCH + c) * LW + h * 128 + 16 * n + fr) * 2) = (f32x2){Arun[n], Hrun[n]};
;     }
	v_pk_fma_f32 v[160:161], v[56:57], v[86:87], v[88:89]
	v_pk_mul_f32 v[164:165], v[164:165], v[54:55]
	v_mfma_f32_16x16x32_bf16 v[54:57], v[50:53], v[2:5], 0
	v_mul_f32_e64 v58, v58, v62
	v_mul_f32_e64 v59, v59, v63
	v_mfma_f32_16x16x32_bf16 v[50:53], v[50:53], v[6:9], 0
	s_nop 4
	v_mul_f32_e64 v54, v58, v54
	v_mul_f32_e64 v55, v59, v55
	v_add_f32_e32 v58, v190, v64
	v_mul_f32_e32 v58, 0xbfb8aa3b, v58
	v_exp_f32_e32 v58, v58
	v_fmac_f32_e32 v55, v67, v54
	v_add_f32_e32 v58, 1.0, v58
	v_rcp_f32_e32 v59, v58
	v_add_f32_e32 v58, v192, v60
	v_mul_f32_e32 v58, 0xbfb8aa3b, v58
	v_exp_f32_e32 v58, v58
	v_mul_f32_e32 v59, v194, v59
	v_exp_f32_e32 v63, v59
	v_add_f32_e32 v59, v190, v65
	v_mul_f32_e32 v59, 0xbfb8aa3b, v59
	v_exp_f32_e32 v59, v59
	v_fma_f32 v54, -v63, v63, 1.0
	v_add_f32_e32 v58, 1.0, v58
	v_max_f32_e32 v54, 0, v54
	v_add_f32_e32 v59, 1.0, v59
	v_rcp_f32_e32 v59, v59
	v_rcp_f32_e32 v58, v58
	v_add_f32_e32 v60, v192, v61
	v_sqrt_f32_e32 v62, v54
	v_mul_f32_e32 v59, v194, v59
	v_mul_f32_e32 v60, 0xbfb8aa3b, v60
	v_exp_f32_e32 v65, v59
	v_exp_f32_e32 v60, v60
	v_mov_b32_e32 v59, v55
	v_pk_mul_f32 v[54:55], v[58:59], v[62:63]
	v_add_f32_e32 v59, v193, v95
	v_fmac_f32_e32 v55, v54, v56
	v_fma_f32 v54, -v65, v65, 1.0
	v_add_f32_e32 v60, 1.0, v60
	v_max_f32_e32 v54, 0, v54
	v_rcp_f32_e32 v60, v60
	v_sqrt_f32_e32 v64, v54
	v_mov_b32_e32 v61, v55
	v_mul_f32_e32 v59, 0xbfb8aa3b, v59
	v_exp_f32_e32 v59, v59
	v_pk_mul_f32 v[54:55], v[60:61], v[64:65]
	v_add_f32_e32 v61, v193, v96
	v_fmac_f32_e32 v55, v54, v57
	ds_bpermute_b32 v56, v151, v55
	ds_bpermute_b32 v60, v151, v55 offset:64
	ds_bpermute_b32 v64, v151, v55 offset:128
	ds_bpermute_b32 v68, v151, v55 offset:192
	v_add_f32_e32 v55, v191, v98
	v_mul_f32_e32 v55, 0xbfb8aa3b, v55
	v_exp_f32_e32 v55, v55
	v_mul_f32_e32 v54, v67, v66
	v_mul_f32_e32 v54, v63, v54
	v_mul_f32_e32 v57, v65, v54
	v_add_f32_e32 v55, 1.0, v55
	v_rcp_f32_e32 v55, v55
	ds_bpermute_b32 v54, v151, v57
	ds_bpermute_b32 v58, v151, v57 offset:64
	ds_bpermute_b32 v62, v151, v57 offset:128
	ds_bpermute_b32 v66, v151, v57 offset:192
	v_add_f32_e32 v57, v193, v94
	v_mul_f32_e32 v57, 0xbfb8aa3b, v57
	v_exp_f32_e32 v57, v57
	v_mul_f32_e32 v55, v195, v55
	v_exp_f32_e32 v55, v55
	v_add_f32_e32 v59, 1.0, v59
	v_add_f32_e32 v57, 1.0, v57
	v_rcp_f32_e32 v70, v57
	v_fma_f32 v57, -v55, v55, 1.0
	v_max_f32_e32 v57, 0, v57
	v_sqrt_f32_e32 v72, v57
	v_add_f32_e32 v57, v191, v99
	v_mul_f32_e32 v57, 0xbfb8aa3b, v57
	v_exp_f32_e32 v57, v57
	v_rcp_f32_e32 v71, v59
	v_mul_f32_e32 v61, 0xbfb8aa3b, v61
	v_exp_f32_e32 v61, v61
	v_add_f32_e32 v57, 1.0, v57
	v_rcp_f32_e32 v57, v57
	v_add_f32_e32 v61, 1.0, v61
	v_mul_f32_e32 v57, v195, v57
	v_exp_f32_e32 v57, v57
	s_nop 0
	v_fma_f32 v59, -v57, v57, 1.0
	v_max_f32_e32 v59, 0, v59
	v_sqrt_f32_e32 v73, v59
	v_add_f32_e32 v59, v191, v100
	v_mul_f32_e32 v59, 0xbfb8aa3b, v59
	v_exp_f32_e32 v59, v59
	v_pk_mul_f32 v[70:71], v[70:71], v[72:73]
	v_add_f32_e32 v59, 1.0, v59
	v_rcp_f32_e32 v59, v59
	v_pk_mul_f32 v[50:51], v[70:71], v[50:51]
	v_rcp_f32_e32 v70, v61
	v_fmac_f32_e32 v51, v57, v50
	v_mul_f32_e32 v59, v195, v59
	v_exp_f32_e32 v73, v59
	v_add_f32_e32 v59, v191, v101
	v_mul_f32_e32 v59, 0xbfb8aa3b, v59
	v_exp_f32_e32 v59, v59
	v_fma_f32 v50, -v73, v73, 1.0
	v_max_f32_e32 v50, 0, v50
	v_add_f32_e32 v61, v193, v97
	v_add_f32_e32 v59, 1.0, v59
	v_rcp_f32_e32 v59, v59
	v_sqrt_f32_e32 v72, v50
	v_mul_f32_e32 v61, 0xbfb8aa3b, v61
	v_exp_f32_e32 v61, v61
	v_mul_f32_e32 v59, v195, v59
	v_exp_f32_e32 v77, v59
	v_mov_b32_e32 v71, v51
	v_pk_mul_f32 v[50:51], v[70:71], v[72:73]
	v_add_f32_e32 v61, 1.0, v61
	v_fmac_f32_e32 v51, v50, v52
	v_fma_f32 v50, -v77, v77, 1.0
	v_max_f32_e32 v50, 0, v50
	v_rcp_f32_e32 v74, v61
	v_sqrt_f32_e32 v76, v50
	v_mov_b32_e32 v75, v51
	v_pk_mul_f32 v[50:51], v[74:75], v[76:77]
	s_nop 0
	v_fmac_f32_e32 v51, v50, v53
	v_mul_f32_e32 v50, v57, v55
	v_mul_f32_e32 v50, v73, v50
	v_mul_f32_e32 v50, v77, v50
	ds_bpermute_b32 v55, v151, v50
	ds_bpermute_b32 v59, v151, v50 offset:64
	ds_bpermute_b32 v63, v151, v50 offset:128
	ds_bpermute_b32 v67, v151, v50 offset:192
	ds_bpermute_b32 v57, v151, v51
	ds_bpermute_b32 v61, v151, v51 offset:64
	ds_bpermute_b32 v65, v151, v51 offset:128
	ds_bpermute_b32 v69, v151, v51 offset:192
	s_waitcnt lgkmcnt(6)
	v_pk_mul_f32 v[50:51], v[54:55], v[58:59]
	s_waitcnt lgkmcnt(4)
	v_pk_mul_f32 v[52:53], v[62:63], v[66:67]
	s_nop 0
	v_pk_mul_f32 v[50:51], v[50:51], v[52:53]
	s_waitcnt lgkmcnt(3)
	v_pk_fma_f32 v[52:53], v[156:157], v[54:55], v[56:57]
	v_pk_mul_f32 v[158:159], v[158:159], v[50:51]
	s_waitcnt lgkmcnt(2)
	v_pk_fma_f32 v[52:53], v[52:53], v[58:59], v[60:61]
	s_waitcnt lgkmcnt(1)
	v_pk_fma_f32 v[52:53], v[52:53], v[62:63], v[64:65]
	s_waitcnt lgkmcnt(0)
	v_pk_fma_f32 v[156:157], v[52:53], v[66:67], v[68:69]
	s_cbranch_vccz .LBB0_668
	s_and_saveexec_b64 s[28:29], s[4:5]
	s_cbranch_execz .LBB0_666
	s_ashr_i32 s59, s58, 31
	s_lshl_b64 s[16:17], s[58:59], 6
	s_ashr_i32 s2, s11, 31
	s_add_u32 s3, s16, s11
	s_addc_u32 s2, s17, s2
	s_mulk_i32 s2, 0x500
	v_mad_u64_u32 v[10:11], s[16:17], s3, v217, v[152:153]
	v_add_u32_e32 v11, s2, v11
	v_mov_b32_e32 v12, v163
	v_mov_b32_e32 v13, v173
	v_lshl_add_u64 v[10:11], v[10:11], 3, s[94:95]
	global_store_dwordx2 v[10:11], v[12:13], off sc1
	v_mov_b32_e32 v12, v168
	v_mov_b32_e32 v13, v166
	global_store_dwordx2 v[10:11], v[12:13], off offset:256 sc1
	v_mov_b32_e32 v12, v164
	v_mov_b32_e32 v13, v160
	v_mov_b32_e32 v163, v172
	v_mov_b32_e32 v166, v169
	global_store_dwordx2 v[10:11], v[12:13], off offset:512 sc1
	v_mov_b32_e32 v160, v165
	v_mov_b32_e32 v12, v158
	v_mov_b32_e32 v13, v156
	v_mov_b32_e32 v156, v159
	global_store_dwordx2 v[10:11], v[162:163], off offset:128 sc1
	global_store_dwordx2 v[10:11], v[166:167], off offset:384 sc1
	global_store_dwordx2 v[10:11], v[160:161], off offset:640 sc1
	global_store_dwordx2 v[10:11], v[12:13], off offset:768 sc1
	global_store_dwordx2 v[10:11], v[156:157], off offset:896 sc1
	s_branch .LBB0_666
